# code placement: 64-byte alignment of the GEMM K-loop, diff-attention and NA loop heads
# baseline (speedup 1.0000x reference)
.LBB0_175:
	s_mov_b32 s28, s29
	s_ashr_i32 s29, s29, 31
	s_lshl_b64 s[34:35], s[28:29], 20
	s_add_u32 s34, s90, s34
	s_addc_u32 s35, s91, s35
	s_and_b64 s[36:37], s[30:31], exec
	s_mov_b32 s26, s27
	s_cselect_b32 s2, s35, s43
	s_cselect_b32 s29, s34, s42
	s_ashr_i32 s27, s27, 31
	s_lshl_b64 s[36:37], s[26:27], 20
	s_add_u32 s36, s92, s36
	s_addc_u32 s37, s93, s37
	s_and_b64 s[44:45], s[30:31], exec
	s_cselect_b32 s27, s37, s41
	s_cselect_b32 s39, s36, s40
	s_add_u32 s46, s40, 0x100
	s_addc_u32 s47, s41, 0
	s_add_u32 s40, s42, 0x80080
	v_mov_b32_e32 v2, 0
	s_addc_u32 s41, s43, 0
	s_mov_b32 s52, -2
	v_mov_b32_e32 v3, v2
	v_mov_b64_e32 v[4:5], v[2:3]
	v_mov_b64_e32 v[6:7], v[2:3]
	v_mov_b64_e32 v[8:9], v[2:3]
	v_mov_b64_e32 v[18:19], v[2:3]
	v_mov_b64_e32 v[20:21], v[2:3]
	v_mov_b64_e32 v[22:23], v[2:3]
	v_mov_b64_e32 v[24:25], v[2:3]
	v_mov_b64_e32 v[34:35], v[2:3]
	v_mov_b64_e32 v[36:37], v[2:3]
	v_mov_b64_e32 v[38:39], v[2:3]
	v_mov_b64_e32 v[40:41], v[2:3]
	v_mov_b64_e32 v[50:51], v[2:3]
	v_mov_b64_e32 v[52:53], v[2:3]
	v_mov_b64_e32 v[54:55], v[2:3]
	v_mov_b64_e32 v[56:57], v[2:3]
	v_mov_b64_e32 v[10:11], v[2:3]
	v_mov_b64_e32 v[12:13], v[2:3]
	v_mov_b64_e32 v[14:15], v[2:3]
	v_mov_b64_e32 v[16:17], v[2:3]
	v_mov_b64_e32 v[26:27], v[2:3]
	v_mov_b64_e32 v[28:29], v[2:3]
	v_mov_b64_e32 v[30:31], v[2:3]
	v_mov_b64_e32 v[32:33], v[2:3]
	v_mov_b64_e32 v[42:43], v[2:3]
	v_mov_b64_e32 v[44:45], v[2:3]
	v_mov_b64_e32 v[46:47], v[2:3]
	v_mov_b64_e32 v[48:49], v[2:3]
	v_mov_b64_e32 v[66:67], v[2:3]
	v_mov_b64_e32 v[68:69], v[2:3]
	v_mov_b64_e32 v[70:71], v[2:3]
	v_mov_b64_e32 v[72:73], v[2:3]
	v_mov_b64_e32 v[74:75], v[2:3]
	v_mov_b64_e32 v[76:77], v[2:3]
	v_mov_b64_e32 v[86:87], v[2:3]
	v_mov_b64_e32 v[88:89], v[2:3]
	v_mov_b64_e32 v[98:99], v[2:3]
	v_mov_b64_e32 v[100:101], v[2:3]
	v_mov_b64_e32 v[110:111], v[2:3]
	v_mov_b64_e32 v[112:113], v[2:3]
	v_mov_b64_e32 v[130:131], v[2:3]
	v_mov_b64_e32 v[132:133], v[2:3]
	v_mov_b64_e32 v[134:135], v[2:3]
	v_mov_b64_e32 v[136:137], v[2:3]
	v_mov_b64_e32 v[154:155], v[2:3]
	v_mov_b64_e32 v[156:157], v[2:3]
	v_mov_b64_e32 v[158:159], v[2:3]
	v_mov_b64_e32 v[160:161], v[2:3]
	v_mov_b64_e32 v[90:91], v[2:3]
	v_mov_b64_e32 v[92:93], v[2:3]
	v_mov_b64_e32 v[94:95], v[2:3]
	v_mov_b64_e32 v[96:97], v[2:3]
	v_mov_b64_e32 v[114:115], v[2:3]
	v_mov_b64_e32 v[116:117], v[2:3]
	v_mov_b64_e32 v[118:119], v[2:3]
	v_mov_b64_e32 v[120:121], v[2:3]
	v_mov_b64_e32 v[138:139], v[2:3]
	v_mov_b64_e32 v[140:141], v[2:3]
	v_mov_b64_e32 v[142:143], v[2:3]
	v_mov_b64_e32 v[144:145], v[2:3]
	v_mov_b64_e32 v[162:163], v[2:3]
	v_mov_b64_e32 v[164:165], v[2:3]
	v_mov_b64_e32 v[166:167], v[2:3]
	v_mov_b64_e32 v[168:169], v[2:3]
	v_add_u32_e32 v212, 0x18000, v218
	v_add_u32_e32 v213, 0x1c000, v218
	.p2align	6

; __device__ __forceinline__ bf16x8 kld(lds_cptr p) { return *(const __attribute__((address_space(3))) bf16x8*)p; }
; #define WAIT_BAR(N) asm volatile("s_waitcnt vmcnt(" #N ") lgkmcnt(0)\n\ts_barrier" ::: "memory")
; #define SJ_ISSUE() do { if (sj < SJ.n) { att::side_issue(SJ, sj, wid, lane, shm); sjp = true; sji = true; } } while (0)
; #define SJ_WAIT_BAR() do { if (sji) { WAIT_BAR(5); sji = false; } else { WAIT_BAR(3); } } while (0)
; #define DMA_K(t_, slot) att::glds16(ksrc + (size_t)(t_) * 8 * 512, (unsigned)__builtin_amdgcn_readfirstlane(kdst + (slot)))
; #define DMA_V(t_, slot) do { att::glds16(vsrc + (size_t)(t_) * 16 * 512, (unsigned)__builtin_amdgcn_readfirstlane(vdst + (slot))); \
;     att::glds16(vsrc + (size_t)(t_) * 16 * 512 + 512, (unsigned)__builtin_amdgcn_readfirstlane(vdst + (slot) + 1024)); } while (0)
; #define ROT() do { sl_prev = sl_cur; sl_cur = sl_next; sl_next = (sl_next == 2 * VSLOT) ? 0 : sl_next + VSLOT; } while (0)
; template <int THRL> ...
;     ...
;       for (int r = 0; r < 16; ++r) { pA0[r] = __builtin_amdgcn_exp2f(pA0[r] - rm); pA1[r] = __builtin_amdgcn_exp2f(pA1[r] - rm); }
; #pragma unroll
;       for (int r = 0; r < 16; ++r) negm[r] = -mhat;
;       asm volatile("" : "+v"(negm)); }
;     WAIT_BAR(0);
;     SJ_ISSUE(); DMA_K(3, KSL(3)); DMA_V(1, VSLOT);
;     ROT();
;     bf16x8 kq0, kq1, kq2, kq3, qq0, qq1;
;     kq0 = kld(kp0 + KSL(1)); kq1 = kld(kp0 + KSL(1) + 512); kq2 = kld(kp0 + KSL(1) + 2048); qq0 = kld(qp0);
;     SJ_WAIT_BAR();
.LBB0_417:
	v_sub_f32_e32 v18, v18, v149
	v_exp_f32_e32 v203, v18
	v_sub_f32_e32 v18, v35, v149
	v_exp_f32_e32 v99, v18
	v_sub_f32_e32 v18, v19, v149
	v_exp_f32_e32 v206, v18
	v_sub_f32_e32 v18, v36, v149
	v_exp_f32_e32 v127, v18
	v_sub_f32_e32 v18, v20, v149
	v_exp_f32_e32 v212, v18
	v_sub_f32_e32 v18, v37, v149
	v_exp_f32_e32 v223, v18
	v_sub_f32_e32 v18, v21, v149
	v_exp_f32_e32 v213, v18
	v_sub_f32_e32 v18, v38, v149
	v_exp_f32_e32 v217, v18
	v_sub_f32_e32 v18, v22, v149
	v_exp_f32_e32 v142, v18
	v_sub_f32_e32 v18, v39, v149
	v_exp_f32_e32 v219, v18
	v_sub_f32_e32 v18, v23, v149
	v_exp_f32_e32 v209, v18
	v_sub_f32_e32 v18, v40, v149
	v_exp_f32_e32 v222, v18
	v_sub_f32_e32 v18, v24, v149
	v_exp_f32_e32 v204, v18
	v_sub_f32_e32 v18, v41, v149
	v_exp_f32_e32 v224, v18
	v_sub_f32_e32 v18, v25, v149
	v_exp_f32_e32 v207, v18
	v_sub_f32_e32 v18, v42, v149
	v_exp_f32_e32 v214, v18
	v_sub_f32_e32 v18, v26, v149
	v_exp_f32_e32 v144, v18
	v_sub_f32_e32 v18, v43, v149
	v_exp_f32_e32 v122, v18
	v_sub_f32_e32 v18, v27, v149
	v_exp_f32_e32 v202, v18
	v_sub_f32_e32 v18, v44, v149
	v_exp_f32_e32 v123, v18
	v_sub_f32_e32 v18, v28, v149
	v_exp_f32_e32 v205, v18
	v_sub_f32_e32 v18, v45, v149
	v_exp_f32_e32 v220, v18
	v_sub_f32_e32 v18, v29, v149
	v_exp_f32_e32 v210, v18
	v_sub_f32_e32 v18, v46, v149
	v_exp_f32_e32 v216, v18
	v_sub_f32_e32 v18, v30, v149
	v_exp_f32_e32 v143, v18
	v_sub_f32_e32 v18, v47, v149
	v_exp_f32_e32 v218, v18
	v_sub_f32_e32 v18, v31, v149
	v_exp_f32_e32 v145, v18
	v_sub_f32_e32 v18, v48, v149
	v_exp_f32_e32 v215, v18
	v_sub_f32_e32 v18, v32, v149
	v_exp_f32_e32 v208, v18
	v_sub_f32_e32 v18, v49, v149
	v_sub_f32_e32 v34, v34, v149
	v_exp_f32_e32 v221, v18
	v_sub_f32_e32 v18, v33, v149
	v_exp_f32_e32 v98, v34
	v_exp_f32_e32 v211, v18
	s_add_i32 s30, s72, s2
	s_ashr_i32 s31, s30, 31
	s_lshl_b64 s[30:31], s[30:31], 19
	v_lshl_add_u64 v[178:179], v[50:51], 0, s[18:19]
	v_mov_b64_e32 v[64:65], v[16:17]
	v_mov_b64_e32 v[48:49], v[16:17]
	v_mov_b64_e32 v[32:33], v[16:17]
	s_xor_b64 s[26:27], s[26:27], -1
	v_lshl_add_u64 v[176:177], v[172:173], 0, s[30:31]
	s_mov_b32 s2, 0x8000
	s_movk_i32 s0, 0x4000
	s_mov_b32 s34, 0
	v_mov_b32_e32 v146, 0
	s_mov_b32 s54, -1
	s_mov_b64 s[30:31], 0
	v_mov_b64_e32 v[180:181], v[174:175]
	v_mov_b64_e32 v[62:63], v[14:15]
	v_mov_b64_e32 v[60:61], v[12:13]
	v_mov_b64_e32 v[58:59], v[10:11]
	v_mov_b64_e32 v[56:57], v[8:9]
	v_mov_b64_e32 v[54:55], v[6:7]
	v_mov_b64_e32 v[52:53], v[4:5]
	v_mov_b64_e32 v[50:51], v[2:3]
	v_mov_b64_e32 v[46:47], v[14:15]
	v_mov_b64_e32 v[44:45], v[12:13]
	v_mov_b64_e32 v[42:43], v[10:11]
	v_mov_b64_e32 v[40:41], v[8:9]
	v_mov_b64_e32 v[38:39], v[6:7]
	v_mov_b64_e32 v[36:37], v[4:5]
	v_mov_b64_e32 v[34:35], v[2:3]
	v_mov_b64_e32 v[30:31], v[14:15]
	v_mov_b64_e32 v[28:29], v[12:13]
	v_mov_b64_e32 v[26:27], v[10:11]
	v_mov_b64_e32 v[24:25], v[8:9]
	v_mov_b64_e32 v[22:23], v[6:7]
	v_mov_b64_e32 v[20:21], v[4:5]
	v_mov_b64_e32 v[18:19], v[2:3]
	.p2align	6

.LBB0_518:
	s_add_i32 s2, s2, 2
	v_add_u32_e32 v193, 0x400, v193
	v_lshl_add_u64 v[152:153], v[152:153], 0, s[60:61]
	v_lshl_add_u64 v[154:155], v[154:155], 0, s[60:61]
	v_lshl_add_u64 v[156:157], v[156:157], 0, s[60:61]
	v_lshl_add_u64 v[158:159], v[158:159], 0, s[60:61]
	s_waitcnt lgkmcnt(0)
	s_barrier
	s_and_b64 vcc, exec, s[64:65]
	s_cbranch_vccnz .LBB0_542
	.p2align	6

.LBB0_547:
	s_add_i32 s55, s55, 2
	v_add_u32_e32 v150, 0x400, v150
	v_lshl_add_u64 v[130:131], v[130:131], 0, s[60:61]
	v_lshl_add_u64 v[132:133], v[132:133], 0, s[60:61]
	v_lshl_add_u64 v[134:135], v[134:135], 0, s[60:61]
	v_lshl_add_u64 v[136:137], v[136:137], 0, s[60:61]
	s_waitcnt lgkmcnt(0)
	s_barrier
	s_and_b64 vcc, exec, s[48:49]
	s_cbranch_vccnz .LBB0_572
	.p2align	6

.LBB0_650:
	s_ashr_i32 s15, s14, 31
	s_lshl_b64 s[18:19], s[14:15], 20
	s_add_u32 s18, s92, s18
	s_addc_u32 s19, s93, s19
	s_and_b64 s[20:21], s[16:17], exec
	s_cselect_b32 s15, s19, s29
	s_cselect_b32 s23, s18, s28
	s_ashr_i32 s13, s12, 31
	s_lshl_b64 s[20:21], s[12:13], 20
	s_add_u32 s20, s94, s20
	s_addc_u32 s21, s95, s21
	s_and_b64 s[30:31], s[16:17], exec
	s_cselect_b32 s13, s21, s27
	s_cselect_b32 s43, s20, s26
	s_add_u32 s44, s26, 0x100
	s_addc_u32 s45, s27, 0
	s_add_u32 s26, s28, 0x80080
	v_mov_b32_e32 v2, 0
	s_addc_u32 s27, s29, 0
	s_mov_b32 s46, -2
	s_waitcnt lgkmcnt(0)
	v_mov_b32_e32 v3, v2
	v_mov_b64_e32 v[4:5], v[2:3]
	v_mov_b64_e32 v[6:7], v[2:3]
	v_mov_b64_e32 v[8:9], v[2:3]
	v_mov_b64_e32 v[18:19], v[2:3]
	v_mov_b64_e32 v[20:21], v[2:3]
	v_mov_b64_e32 v[22:23], v[2:3]
	v_mov_b64_e32 v[24:25], v[2:3]
	v_mov_b64_e32 v[34:35], v[2:3]
	v_mov_b64_e32 v[36:37], v[2:3]
	v_mov_b64_e32 v[38:39], v[2:3]
	v_mov_b64_e32 v[40:41], v[2:3]
	v_mov_b64_e32 v[50:51], v[2:3]
	v_mov_b64_e32 v[52:53], v[2:3]
	v_mov_b64_e32 v[54:55], v[2:3]
	v_mov_b64_e32 v[56:57], v[2:3]
	v_mov_b64_e32 v[10:11], v[2:3]
	v_mov_b64_e32 v[12:13], v[2:3]
	v_mov_b64_e32 v[14:15], v[2:3]
	v_mov_b64_e32 v[16:17], v[2:3]
	v_mov_b64_e32 v[26:27], v[2:3]
	v_mov_b64_e32 v[28:29], v[2:3]
	v_mov_b64_e32 v[30:31], v[2:3]
	v_mov_b64_e32 v[32:33], v[2:3]
	v_mov_b64_e32 v[42:43], v[2:3]
	v_mov_b64_e32 v[44:45], v[2:3]
	v_mov_b64_e32 v[46:47], v[2:3]
	v_mov_b64_e32 v[48:49], v[2:3]
	v_mov_b64_e32 v[58:59], v[2:3]
	v_mov_b64_e32 v[60:61], v[2:3]
	v_mov_b64_e32 v[62:63], v[2:3]
	v_mov_b64_e32 v[64:65], v[2:3]
	v_mov_b64_e32 v[66:67], v[2:3]
	v_mov_b64_e32 v[68:69], v[2:3]
	v_mov_b64_e32 v[70:71], v[2:3]
	v_mov_b64_e32 v[72:73], v[2:3]
	v_mov_b64_e32 v[82:83], v[2:3]
	v_mov_b64_e32 v[84:85], v[2:3]
	v_mov_b64_e32 v[86:87], v[2:3]
	v_mov_b64_e32 v[88:89], v[2:3]
	v_mov_b64_e32 v[98:99], v[2:3]
	v_mov_b64_e32 v[100:101], v[2:3]
	v_mov_b64_e32 v[102:103], v[2:3]
	v_mov_b64_e32 v[104:105], v[2:3]
	v_mov_b64_e32 v[114:115], v[2:3]
	v_mov_b64_e32 v[116:117], v[2:3]
	v_mov_b64_e32 v[118:119], v[2:3]
	v_mov_b64_e32 v[120:121], v[2:3]
	v_mov_b64_e32 v[74:75], v[2:3]
	v_mov_b64_e32 v[76:77], v[2:3]
	v_mov_b64_e32 v[78:79], v[2:3]
	v_mov_b64_e32 v[80:81], v[2:3]
	v_mov_b64_e32 v[90:91], v[2:3]
	v_mov_b64_e32 v[92:93], v[2:3]
	v_mov_b64_e32 v[94:95], v[2:3]
	v_mov_b64_e32 v[96:97], v[2:3]
	v_mov_b64_e32 v[106:107], v[2:3]
	v_mov_b64_e32 v[108:109], v[2:3]
	v_mov_b64_e32 v[110:111], v[2:3]
	v_mov_b64_e32 v[112:113], v[2:3]
	v_mov_b64_e32 v[122:123], v[2:3]
	v_mov_b64_e32 v[124:125], v[2:3]
	v_mov_b64_e32 v[126:127], v[2:3]
	v_mov_b64_e32 v[128:129], v[2:3]
	v_add_u32_e32 v192, 0x18000, v195
	v_add_u32_e32 v193, 0x1c000, v195
	.p2align	6

.LBB0_807:
	s_mov_b32 s18, s19
	s_ashr_i32 s19, s19, 31
	s_lshl_b64 s[22:23], s[18:19], 20
	s_add_u32 s22, s70, s22
	s_addc_u32 s23, s71, s23
	s_and_b64 s[24:25], s[20:21], exec
	s_mov_b32 s16, s17
	s_cselect_b32 s19, s23, s35
	s_cselect_b32 s51, s22, s34
	s_ashr_i32 s17, s17, 31
	s_lshl_b64 s[24:25], s[16:17], 20
	s_add_u32 s24, s84, s24
	s_addc_u32 s25, s85, s25
	s_and_b64 s[36:37], s[20:21], exec
	s_cselect_b32 s17, s25, s31
	s_cselect_b32 s52, s24, s30
	s_add_u32 s53, s30, 0x100
	s_addc_u32 s54, s31, 0
	s_add_u32 s30, s34, 0x80080
	v_mov_b32_e32 v2, 0
	s_addc_u32 s31, s35, 0
	s_mov_b32 s55, -2
	v_mov_b32_e32 v3, v2
	v_mov_b64_e32 v[4:5], v[2:3]
	v_mov_b64_e32 v[6:7], v[2:3]
	v_mov_b64_e32 v[8:9], v[2:3]
	v_mov_b64_e32 v[18:19], v[2:3]
	v_mov_b64_e32 v[20:21], v[2:3]
	v_mov_b64_e32 v[22:23], v[2:3]
	v_mov_b64_e32 v[24:25], v[2:3]
	v_mov_b64_e32 v[34:35], v[2:3]
	v_mov_b64_e32 v[36:37], v[2:3]
	v_mov_b64_e32 v[38:39], v[2:3]
	v_mov_b64_e32 v[40:41], v[2:3]
	v_mov_b64_e32 v[50:51], v[2:3]
	v_mov_b64_e32 v[52:53], v[2:3]
	v_mov_b64_e32 v[54:55], v[2:3]
	v_mov_b64_e32 v[56:57], v[2:3]
	v_mov_b64_e32 v[10:11], v[2:3]
	v_mov_b64_e32 v[12:13], v[2:3]
	v_mov_b64_e32 v[14:15], v[2:3]
	v_mov_b64_e32 v[16:17], v[2:3]
	v_mov_b64_e32 v[26:27], v[2:3]
	v_mov_b64_e32 v[28:29], v[2:3]
	v_mov_b64_e32 v[30:31], v[2:3]
	v_mov_b64_e32 v[32:33], v[2:3]
	v_mov_b64_e32 v[42:43], v[2:3]
	v_mov_b64_e32 v[44:45], v[2:3]
	v_mov_b64_e32 v[46:47], v[2:3]
	v_mov_b64_e32 v[48:49], v[2:3]
	v_mov_b64_e32 v[58:59], v[2:3]
	v_mov_b64_e32 v[60:61], v[2:3]
	v_mov_b64_e32 v[62:63], v[2:3]
	v_mov_b64_e32 v[64:65], v[2:3]
	v_mov_b64_e32 v[66:67], v[2:3]
	v_mov_b64_e32 v[68:69], v[2:3]
	v_mov_b64_e32 v[70:71], v[2:3]
	v_mov_b64_e32 v[72:73], v[2:3]
	v_mov_b64_e32 v[82:83], v[2:3]
	v_mov_b64_e32 v[84:85], v[2:3]
	v_mov_b64_e32 v[86:87], v[2:3]
	v_mov_b64_e32 v[88:89], v[2:3]
	v_mov_b64_e32 v[98:99], v[2:3]
	v_mov_b64_e32 v[100:101], v[2:3]
	v_mov_b64_e32 v[102:103], v[2:3]
	v_mov_b64_e32 v[104:105], v[2:3]
	v_mov_b64_e32 v[114:115], v[2:3]
	v_mov_b64_e32 v[116:117], v[2:3]
	v_mov_b64_e32 v[118:119], v[2:3]
	v_mov_b64_e32 v[120:121], v[2:3]
	v_mov_b64_e32 v[74:75], v[2:3]
	v_mov_b64_e32 v[76:77], v[2:3]
	v_mov_b64_e32 v[78:79], v[2:3]
	v_mov_b64_e32 v[80:81], v[2:3]
	v_mov_b64_e32 v[90:91], v[2:3]
	v_mov_b64_e32 v[92:93], v[2:3]
	v_mov_b64_e32 v[94:95], v[2:3]
	v_mov_b64_e32 v[96:97], v[2:3]
	v_mov_b64_e32 v[106:107], v[2:3]
	v_mov_b64_e32 v[108:109], v[2:3]
	v_mov_b64_e32 v[110:111], v[2:3]
	v_mov_b64_e32 v[112:113], v[2:3]
	v_mov_b64_e32 v[122:123], v[2:3]
	v_mov_b64_e32 v[124:125], v[2:3]
	v_mov_b64_e32 v[126:127], v[2:3]
	v_mov_b64_e32 v[128:129], v[2:3]
	v_add_u32_e32 v148, 0x18000, v150
	v_add_u32_e32 v149, 0x1c000, v150
	.p2align	6

.LBB0_1030:
	v_and_b32_e32 v1, 15, v0
	v_and_b32_e32 v14, 48, v0
	v_lshlrev_b32_e32 v16, 2, v0
	s_lshl_b32 s24, s4, 6
	v_lshl_or_b32 v15, v1, 6, v14
	s_lshl_b32 s4, s4, 13
	v_and_b32_e32 v16, 32, v16
	s_and_b32 s18, s17, 3
	v_bitop3_b32 v15, v15, s4, v16 bitop3:0xde
	v_lshlrev_b32_e32 v17, 6, v0
	s_movk_i32 s4, 0x3c0
	v_and_or_b32 v14, v17, s4, v14
	s_lshl_b32 s4, s18, 12
	v_bitop3_b32 v14, s4, v14, v16 bitop3:0xf6
	s_mov_b64 s[4:5], 0x80
	s_add_i32 m0, s20, 0x18000
	v_lshl_add_u64 v[8:9], v[8:9], 0, s[4:5]
	s_waitcnt vmcnt(2)
	s_barrier
	global_load_lds_dwordx4 v[8:9], off
	v_lshl_add_u64 v[6:7], v[6:7], 0, s[4:5]
	s_add_i32 m0, s20, 0x1a000
	s_add_i32 s25, s20, 0x8000
	s_add_i32 s26, s20, 0xa000
	global_load_lds_dwordx4 v[6:7], off
	v_lshl_add_u64 v[4:5], v[4:5], 0, s[4:5]
	s_mov_b32 m0, s25
	s_add_u32 s8, s0, 0x200080
	global_load_lds_dwordx4 v[4:5], off
	v_lshl_add_u64 v[2:3], v[2:3], 0, s[4:5]
	s_mov_b32 m0, s26
	s_addc_u32 s9, s1, 0
	global_load_lds_dwordx4 v[2:3], off
	s_add_i32 m0, s20, 0x1c000
	v_lshl_add_u64 v[2:3], s[8:9], 0, v[130:131]
	global_load_lds_dwordx4 v[2:3], off
	v_lshl_add_u64 v[2:3], s[8:9], 0, v[132:133]
	s_add_i32 m0, s20, 0x1e000
	s_add_u32 s8, s70, s13
	global_load_lds_dwordx4 v[2:3], off
	s_addc_u32 s9, s71, 0
	s_add_u32 s27, s8, 0xc000100
	v_lshlrev_b32_e32 v2, 11, v0
	s_addc_u32 s28, s9, 0
	v_and_b32_e32 v2, 0xc0000, v2
	v_lshlrev_b32_e32 v4, 14, v13
	s_add_u32 s8, s70, s10
	v_or3_b32 v2, v10, v2, v4
	s_addc_u32 s9, s71, s11
	v_add_u32_e32 v2, v2, v11
	v_mov_b32_e32 v3, v131
	v_lshl_add_u64 v[2:3], s[8:9], 0, v[2:3]
	s_mov_b64 s[10:11], 0x2200080
	v_lshl_add_u64 v[134:135], v[2:3], 0, s[10:11]
	v_lshlrev_b32_e32 v2, 7, v12
	v_and_b32_e32 v2, 0x1c0000, v2
	v_or3_b32 v2, v10, v2, v4
	s_waitcnt vmcnt(6)
	v_add_u32_e32 v2, v2, v11
	v_mov_b32_e32 v3, v131
	s_add_i32 s34, 0, 0x10000
	s_add_i32 s36, 0, 0x14000
	s_add_i32 s38, 0, 0x18000
	s_add_i32 s40, 0, 0x1c000
	v_lshl_add_u64 v[2:3], s[8:9], 0, v[2:3]
	v_add_u32_e32 v139, s34, v14
	v_add_u32_e32 v140, s36, v14
	s_add_i32 s34, s34, s12
	s_add_i32 s36, s36, s12
	v_add_u32_e32 v142, s38, v14
	v_add_u32_e32 v143, s40, v14
	s_add_i32 s38, s38, s12
	s_add_i32 s40, s40, s12
	v_readlane_b32 s44, v242, 16
	v_lshrrev_b32_e32 v138, 2, v0
	v_or_b32_e32 v162, s24, v1
	v_lshl_add_u64 v[136:137], v[2:3], 0, s[10:11]
	s_mov_b32 s29, -2
	s_mov_b64 s[10:11], 0
	v_add_u32_e32 v141, 0, v15
	s_add_i32 s30, s20, 0xc000
	s_add_i32 s31, s20, 0xe000
	s_add_i32 s35, s34, 0x2000
	s_add_i32 s37, s36, 0x2000
	s_add_i32 s39, s38, 0x2000
	s_add_i32 s41, s40, 0x2000
	v_mov_b32_e32 v2, v131
	v_mov_b32_e32 v3, v131
	v_mov_b32_e32 v4, v131
	v_mov_b32_e32 v5, v131
	v_mov_b32_e32 v6, v131
	v_mov_b32_e32 v7, v131
	v_mov_b32_e32 v8, v131
	v_mov_b32_e32 v9, v131
	v_mov_b32_e32 v18, v131
	v_mov_b32_e32 v19, v131
	v_mov_b32_e32 v20, v131
	v_mov_b32_e32 v21, v131
	v_mov_b32_e32 v22, v131
	v_mov_b32_e32 v23, v131
	v_mov_b32_e32 v24, v131
	v_mov_b32_e32 v25, v131
	v_mov_b32_e32 v34, v131
	v_mov_b32_e32 v35, v131
	v_mov_b32_e32 v36, v131
	v_mov_b32_e32 v37, v131
	v_mov_b32_e32 v38, v131
	v_mov_b32_e32 v39, v131
	v_mov_b32_e32 v40, v131
	v_mov_b32_e32 v41, v131
	v_mov_b32_e32 v50, v131
	v_mov_b32_e32 v51, v131
	v_mov_b32_e32 v52, v131
	v_mov_b32_e32 v53, v131
	v_mov_b32_e32 v54, v131
	v_mov_b32_e32 v55, v131
	v_mov_b32_e32 v56, v131
	v_mov_b32_e32 v57, v131
	v_mov_b32_e32 v10, v131
	v_mov_b32_e32 v11, v131
	v_mov_b32_e32 v12, v131
	v_mov_b32_e32 v13, v131
	v_mov_b32_e32 v14, v131
	v_mov_b32_e32 v15, v131
	v_mov_b32_e32 v16, v131
	v_mov_b32_e32 v17, v131
	v_mov_b32_e32 v26, v131
	v_mov_b32_e32 v27, v131
	v_mov_b32_e32 v28, v131
	v_mov_b32_e32 v29, v131
	v_mov_b32_e32 v30, v131
	v_mov_b32_e32 v31, v131
	v_mov_b32_e32 v32, v131
	v_mov_b32_e32 v33, v131
	v_mov_b32_e32 v42, v131
	v_mov_b32_e32 v43, v131
	v_mov_b32_e32 v44, v131
	v_mov_b32_e32 v45, v131
	v_mov_b32_e32 v46, v131
	v_mov_b32_e32 v47, v131
	v_mov_b32_e32 v48, v131
	v_mov_b32_e32 v49, v131
	v_mov_b32_e32 v58, v131
	v_mov_b32_e32 v59, v131
	v_mov_b32_e32 v60, v131
	v_mov_b32_e32 v61, v131
	v_mov_b32_e32 v62, v131
	v_mov_b32_e32 v63, v131
	v_mov_b32_e32 v64, v131
	v_mov_b32_e32 v65, v131
	v_mov_b32_e32 v66, v131
	v_mov_b32_e32 v67, v131
	v_mov_b32_e32 v68, v131
	v_mov_b32_e32 v69, v131
	v_mov_b32_e32 v70, v131
	v_mov_b32_e32 v71, v131
	v_mov_b32_e32 v72, v131
	v_mov_b32_e32 v73, v131
	v_mov_b32_e32 v82, v131
	v_mov_b32_e32 v83, v131
	v_mov_b32_e32 v84, v131
	v_mov_b32_e32 v85, v131
	v_mov_b32_e32 v86, v131
	v_mov_b32_e32 v87, v131
	v_mov_b32_e32 v88, v131
	v_mov_b32_e32 v89, v131
	v_mov_b32_e32 v98, v131
	v_mov_b32_e32 v99, v131
	v_mov_b32_e32 v100, v131
	v_mov_b32_e32 v101, v131
	v_mov_b32_e32 v102, v131
	v_mov_b32_e32 v103, v131
	v_mov_b32_e32 v104, v131
	v_mov_b32_e32 v105, v131
	v_mov_b32_e32 v114, v131
	v_mov_b32_e32 v115, v131
	v_mov_b32_e32 v116, v131
	v_mov_b32_e32 v117, v131
	v_mov_b32_e32 v118, v131
	v_mov_b32_e32 v119, v131
	v_mov_b32_e32 v120, v131
	v_mov_b32_e32 v121, v131
	v_mov_b32_e32 v74, v131
	v_mov_b32_e32 v75, v131
	v_mov_b32_e32 v76, v131
	v_mov_b32_e32 v77, v131
	v_mov_b32_e32 v78, v131
	v_mov_b32_e32 v79, v131
	v_mov_b32_e32 v80, v131
	v_mov_b32_e32 v81, v131
	v_mov_b32_e32 v90, v131
	v_mov_b32_e32 v91, v131
	v_mov_b32_e32 v92, v131
	v_mov_b32_e32 v93, v131
	v_mov_b32_e32 v94, v131
	v_mov_b32_e32 v95, v131
	v_mov_b32_e32 v96, v131
	v_mov_b32_e32 v97, v131
	v_mov_b32_e32 v106, v131
	v_mov_b32_e32 v107, v131
	v_mov_b32_e32 v108, v131
	v_mov_b32_e32 v109, v131
	v_mov_b32_e32 v110, v131
	v_mov_b32_e32 v111, v131
	v_mov_b32_e32 v112, v131
	v_mov_b32_e32 v113, v131
	v_mov_b32_e32 v122, v131
	v_mov_b32_e32 v123, v131
	v_mov_b32_e32 v124, v131
	v_mov_b32_e32 v125, v131
	v_mov_b32_e32 v126, v131
	v_mov_b32_e32 v127, v131
	v_mov_b32_e32 v128, v131
	v_mov_b32_e32 v129, v131
	v_readlane_b32 s45, v242, 17
	s_barrier
	.p2align	6
